# same for the second attention unit's two loop copies (K prefetch fix + QK reading the prefetched K directly)
# baseline (speedup 1.0000x reference)
; #define LAS __attribute__((address_space(3)))
; __device__ __forceinline__ void tile_compute(const bf16x8 (&kf)[4], const bf16x8 (&vf)[2][2], const bf16x8 (&qf)[4], unsigned long long w0, unsigned long long w1,
;                                              float shift, f32x16& o0, f32x16& o1, f32x16& zacc, const bf16x8& ones) {
;     ...
;     for (int eg = 0; eg < 2; ++eg) {
;         const unsigned long long w = eg ? w1 : w0;
;         const unsigned wl = (unsigned)w, wh = (unsigned)(w >> 32);
;         float pv[8];
; #pragma unroll
;         for (int p = 0; p < 4; ++p) {
;             pv[p] = (float)((wl >> (8 * p)) & 0xffu) * __builtin_amdgcn_exp2f(st[8 * eg + p]);
;             pv[4 + p] = (float)((wh >> (8 * p)) & 0xffu) * __builtin_amdgcn_exp2f(st[8 * eg + 4 + p]);
;         }
; #pragma unroll
;         for (int p = 0; p < 4; ++p) pw[4 * eg + p] = pk2(pv[2 * p], pv[2 * p + 1]);
;     }
;     const bf16x8 pf0 = __builtin_bit_cast(bf16x8, (u32x4){pw[0], pw[1], pw[2], pw[3]});
;     const bf16x8 pf1 = __builtin_bit_cast(bf16x8, (u32x4){pw[4], pw[5], pw[6], pw[7]});
;     o0 = __builtin_amdgcn_mfma_f32_32x32x16_bf16(vf[0][0], pf0, o0, 0, 0, 0);
;     o1 = __builtin_amdgcn_mfma_f32_32x32x16_bf16(vf[1][0], pf0, o1, 0, 0, 0);
;     zacc = __builtin_amdgcn_mfma_f32_32x32x16_bf16(ones, pf0, zacc, 0, 0, 0);
;     o0 = __builtin_amdgcn_mfma_f32_32x32x16_bf16(vf[0][1], pf1, o0, 0, 0, 0);
;     o1 = __builtin_amdgcn_mfma_f32_32x32x16_bf16(vf[1][1], pf1, o1, 0, 0, 0);
;     zacc = __builtin_amdgcn_mfma_f32_32x32x16_bf16(ones, pf1, zacc, 0, 0, 0);
; __device__ __forceinline__ void attn_task(const AttnP& P, LAS unsigned char* lds, int b, int hd, int qq, int c, float shift, int lane_in) {
;     ...
;     unsigned long long Hp[2], Hn[2], Bp[2], Bn[2], mT0[2], mT3[2], mAp[2], mAn[2], mLp, mLn;
;     { const LAS unsigned long long* T = (const LAS unsigned long long*)(lds + LDS_ATAB + lane * 144);
;       Hp[0] = T[0]; Hp[1] = T[1]; Hn[0] = T[2]; Hn[1] = T[3]; Bp[0] = T[4]; Bp[1] = T[5]; Bn[0] = T[6]; Bn[1] = T[7];
;       mT0[0] = T[8]; mT0[1] = T[9]; mT3[0] = T[10]; mT3[1] = T[11]; mAp[0] = T[12]; mAp[1] = T[13]; mAn[0] = T[14]; mAn[1] = T[15]; mLp = T[16]; mLn = T[17]; }
;     f32x16 o0 = {}, o1 = {}, zacc = {};
;     bf16x8 ones = {0x3F80, 0x3F80, 0x3F80, 0x3F80, 0x3F80, 0x3F80, 0x3F80, 0x3F80}; asm volatile("" : "+v"(ones));
;     int li = 10, ph = 0;
.LBB0_333:
	s_waitcnt lgkmcnt(1)
	v_max_f32_e32 v7, v7, v7
	v_max_f32_e32 v2, v2, v7
	s_waitcnt lgkmcnt(0)
	v_max_f32_e32 v7, v8, v8
	v_max_f32_e32 v6, v6, v7
	v_mul_f32_e32 v2, 0x41000000, v2
	v_mul_f32_e32 v2, v2, v6
	v_mul_lo_u32 v6, v228, s31
	v_add_u32_e32 v6, 0, v6
	v_mul_f32_e32 v2, 0x3fb8aa3b, v2
	v_add_u32_e32 v6, 0x24000, v6
	v_min_f32_e32 v2, 0x42800000, v2
	ds_read_b128 v[118:121], v6
	ds_read_b128 v[122:125], v6 offset:16
	ds_read_b128 v[126:129], v6 offset:32
	ds_read_b128 v[130:133], v6 offset:48
	ds_read_b128 v[134:137], v6 offset:64
	ds_read_b128 v[138:141], v6 offset:80
	ds_read_b128 v[142:145], v6 offset:96
	ds_read_b128 v[146:149], v6 offset:112
	ds_read_b128 v[150:153], v6 offset:128
	s_waitcnt lgkmcnt(8)
	v_mad_u64_u32 v[8:9], s[0:1], v118, 3, 0
	v_cmp_lt_f32_e32 vcc, s30, v2
	v_mov_b32_e32 v10, v9
	v_mad_u64_u32 v[10:11], s[0:1], v119, 3, v[10:11]
	v_cndmask_b32_e32 v2, 0, v2, vcc
	s_nop 0
	v_readfirstlane_b32 s100, v2
	s_nop 1
	v_cmp_class_f32_e64 s[100:101], s100, 64
	s_waitcnt lgkmcnt(7)
	v_sub_co_u32_e32 v8, vcc, v8, v122
	s_lshl_b32 s56, s12, 2
	s_nop 0
	v_subb_co_u32_e32 v9, vcc, v10, v123, vcc
	s_waitcnt lgkmcnt(5)
	v_lshl_add_u64 v[202:203], v[8:9], 0, v[130:131]
	v_mad_u64_u32 v[8:9], s[0:1], v120, 3, 0
	s_xor_b32 s39, s56, 15
	v_mov_b32_e32 v10, v9
	s_and_b64 s[0:1], exec, s[60:61]
	v_mad_u64_u32 v[10:11], s[0:1], v121, 3, v[10:11]
	v_sub_co_u32_e32 v8, vcc, v8, v124
	v_mov_b32_e32 v18, 0
	s_cselect_b32 s24, 3, 10
	v_mov_b64_e32 v[156:157], v[84:85]
	s_add_i32 s57, s56, -4
	s_or_b32 s49, s56, -16
	v_lshlrev_b32_e32 v6, 4, v229
	v_add_u32_e32 v230, 2, v17
	v_subb_co_u32_e32 v9, vcc, v10, v125, vcc
	v_mov_b32_e32 v7, v191
	s_mov_b32 s66, 10
	v_mov_b64_e32 v[154:155], v[82:83]
	v_lshl_add_u32 v200, v17, 4, 0
	v_or_b32_e32 v223, 0xffffffe4, v1
	s_add_i32 s48, s56, -1
	v_or_b32_e32 v224, s57, v1
	v_or_b32_e32 v225, s49, v1
	v_add_u32_e32 v226, s93, v6
	v_add_u32_e32 v227, s57, v17
	v_add_u32_e32 v231, s57, v230
	v_lshl_add_u64 v[204:205], v[8:9], 0, v[132:133]
	v_subrev_u32_e32 v232, 26, v17
	v_lshl_add_u32 v233, v17, 10, v214
	v_or3_b32 v234, v190, v3, s36
	v_lshl_add_u64 v[206:207], v[4:5], 1, s[50:51]
	v_lshl_add_u64 v[208:209], s[52:53], 0, v[6:7]
	s_mov_b32 s87, s39
	s_mov_b32 s86, s39
	s_mov_b32 s22, s39
	s_mov_b32 s23, s39
	s_mov_b32 s94, s39
	s_mov_b32 s95, s39
	s_mov_b32 s96, s39
	v_mov_b32_e32 v1, v2
	v_mov_b32_e32 v4, v2
	v_mov_b32_e32 v3, v2
	v_mov_b32_e32 v6, v2
	v_mov_b32_e32 v5, v2
	v_mov_b32_e32 v8, v2
	v_mov_b32_e32 v7, v2
	s_mov_b32 s8, 0
	s_mov_b64 s[0:1], s[60:61]
	s_mov_b32 s72, s24
	v_mov_b32_e32 v19, v18
	v_mov_b32_e32 v20, v18
	v_mov_b32_e32 v21, v18
	v_mov_b32_e32 v22, v18
	v_mov_b32_e32 v23, v18
	v_mov_b32_e32 v24, v18
	v_mov_b32_e32 v25, v18
	v_mov_b32_e32 v26, v18
	v_mov_b32_e32 v27, v18
	v_mov_b32_e32 v28, v18
	v_mov_b32_e32 v29, v18
	v_mov_b32_e32 v30, v18
	v_mov_b32_e32 v31, v18
	v_mov_b32_e32 v32, v18
	v_mov_b32_e32 v33, v18
	v_mov_b32_e32 v34, v18
	v_mov_b32_e32 v35, v18
	v_mov_b32_e32 v36, v18
	v_mov_b32_e32 v37, v18
	v_mov_b32_e32 v38, v18
	v_mov_b32_e32 v39, v18
	v_mov_b32_e32 v40, v18
	v_mov_b32_e32 v41, v18
	v_mov_b32_e32 v42, v18
	v_mov_b32_e32 v43, v18
	v_mov_b32_e32 v44, v18
	v_mov_b32_e32 v45, v18
	v_mov_b32_e32 v46, v18
	v_mov_b32_e32 v47, v18
	v_mov_b32_e32 v48, v18
	v_mov_b32_e32 v49, v18
	v_mov_b32_e32 v50, v18
	v_mov_b32_e32 v51, v18
	v_mov_b32_e32 v52, v18
	v_mov_b32_e32 v53, v18
	v_mov_b32_e32 v54, v18
	v_mov_b32_e32 v55, v18
	v_mov_b32_e32 v56, v18
	v_mov_b32_e32 v57, v18
	v_mov_b32_e32 v58, v18
	v_mov_b32_e32 v59, v18
	v_mov_b32_e32 v60, v18
	v_mov_b32_e32 v61, v18
	v_mov_b32_e32 v62, v18
	v_mov_b32_e32 v63, v18
	v_mov_b32_e32 v64, v18
	v_mov_b32_e32 v65, v18
	v_mov_b32_e32 v10, v2
	v_mov_b32_e32 v9, v2
	v_mov_b32_e32 v12, v2
	v_mov_b32_e32 v11, v2
	v_mov_b32_e32 v14, v2
	v_mov_b32_e32 v13, v2
	v_mov_b32_e32 v16, v2
	v_mov_b32_e32 v15, v2
	v_mul_lo_u32 v245, v234, s71
	v_add_u32_e32 v245, v245, v200
	s_waitcnt vmcnt(0)
	s_branch .LBB0_335
.LBB0_334:
	v_cvt_f32_ubyte1_e32 v175, v212
	v_cvt_f32_ubyte0_e32 v174, v212
	s_nop 3
	v_exp_f32_e32 v66, v66
	s_nop 3
	v_exp_f32_e32 v67, v67
	v_exp_f32_e32 v70, v70
	v_exp_f32_e32 v71, v71
	v_exp_f32_e32 v68, v68
	v_exp_f32_e32 v69, v69
	v_exp_f32_e32 v72, v72
	v_exp_f32_e32 v73, v73
	v_pk_mul_f32 v[66:67], v[66:67], v[174:175]
	v_cvt_f32_ubyte1_e32 v175, v213
	v_cvt_f32_ubyte0_e32 v174, v213
	v_pk_mul_f32 v[70:71], v[70:71], v[174:175]
	v_cvt_f32_ubyte3_e32 v175, v212
	v_cvt_f32_ubyte2_e32 v174, v212
	v_pk_mul_f32 v[68:69], v[68:69], v[174:175]
	v_cvt_f32_ubyte3_e32 v175, v213
	v_cvt_f32_ubyte2_e32 v174, v213
	v_pk_mul_f32 v[72:73], v[72:73], v[174:175]
	v_cvt_pk_bf16_f32 v66, v66, v67
	v_cvt_pk_bf16_f32 v67, v68, v69
	v_cvt_pk_bf16_f32 v68, v70, v71
	v_exp_f32_e32 v70, v74
	v_exp_f32_e32 v71, v75
	v_cvt_pk_bf16_f32 v69, v72, v73
	v_exp_f32_e32 v72, v78
	v_exp_f32_e32 v73, v79
	s_waitcnt vmcnt(4)
	v_mfma_f32_32x32x16_bf16 v[18:33], v[162:165], v[66:69], v[18:33]
	v_cvt_f32_ubyte1_e32 v75, v210
	v_cvt_f32_ubyte0_e32 v74, v210
	v_mul_f32_e64 v70, v70, v74
	v_mul_f32_e64 v71, v71, v75
	v_cvt_f32_ubyte1_e32 v75, v211
	v_cvt_f32_ubyte0_e32 v74, v211
	v_pk_mul_f32 v[72:73], v[72:73], v[74:75]
	v_exp_f32_e32 v74, v76
	v_mfma_f32_32x32x16_bf16 v[34:49], v[158:161], v[66:69], v[34:49]
	v_exp_f32_e32 v75, v77
	v_exp_f32_e32 v76, v80
	v_exp_f32_e32 v77, v81
	v_cvt_f32_ubyte3_e32 v79, v210
	v_cvt_f32_ubyte2_e32 v78, v210
	v_pk_mul_f32 v[74:75], v[74:75], v[78:79]
	s_cmp_lt_i32 s66, 26
	v_mfma_f32_32x32x16_bf16 v[50:65], v[154:157], v[66:69], v[50:65]
	v_cvt_f32_ubyte3_e32 v67, v211
	v_cvt_f32_ubyte2_e32 v66, v211
	v_mul_f32_e64 v76, v76, v66
	v_mul_f32_e64 v77, v77, v67
	v_cvt_pk_bf16_f32 v66, v70, v71
	v_cvt_pk_bf16_f32 v67, v74, v75
	v_cvt_pk_bf16_f32 v68, v72, v73
	v_cvt_pk_bf16_f32 v69, v76, v77
	s_cselect_b64 s[4:5], -1, 0
	s_cmp_lt_i32 s72, 10
	v_mfma_f32_32x32x16_bf16 v[18:33], v[166:169], v[66:69], v[18:33]
	s_cselect_b64 s[0:1], -1, 0
	s_or_b64 s[4:5], s[4:5], s[0:1]
	s_and_b64 vcc, exec, s[4:5]
	v_mfma_f32_32x32x16_bf16 v[34:49], v[170:173], v[66:69], v[34:49]
	v_mfma_f32_32x32x16_bf16 v[50:65], v[154:157], v[66:69], v[50:65]
	s_cbranch_vccz .LBB0_430

; __device__ __forceinline__ void attn_task(const AttnP& P, LAS unsigned char* lds, int b, int hd, int qq, int c, float shift, int lane_in) {
;     ...
;         if (gi < 10 && (ph >= 2 || li >= 26)) {
;             attn_load_v(P, lds, hb, gi, c, R0, lane, vf);
; #pragma unroll
;             for (int kk = 0; kk < 4; ++kk) kf[kk] = gk[kk];
;             if (gi < 4) {
;                 if (gi == 0) { w0 = mT0[0]; w1 = mT0[1]; } else if (gi == 3) { w0 = mT3[0]; w1 = mT3[1]; } else { w0 = 0x0101010101010101ull; w1 = 0x0101010101010101ull; }
;             } else if (gi < 7) {
;                 const bool pos = c > ((c + 4 * (gi - 3)) & 15);
;                 w0 = pos ? mAp[0] : mAn[0]; w1 = pos ? mAp[1] : mAn[1];
;             } else {
;                 { int cg, Rg; run_desc(gi, h, c, R0, cg, Rg); w0 = (c > cg) ? mLp : mLn; }
;                 { int cg, Rg; run_desc(gi, 2 + h, c, R0, cg, Rg); w1 = (c > cg) ? mLp : mLn; }
;             }
.LBB0_342:
	s_and_b64 vcc, exec, s[0:1]
	s_cbranch_vccz .LBB0_403
	s_cmp_gt_i32 s72, 3
	s_cselect_b64 s[6:7], -1, 0
	s_lshl_b32 s68, s72, 2
	s_sub_i32 s11, s68, 28
	s_cmp_gt_u32 s72, 6
	s_cselect_b64 s[0:1], -1, 0
	s_add_i32 s4, s68, s63
	s_waitcnt lgkmcnt(3)
	v_cndmask_b32_e64 v66, 0, 1, s[0:1]
	s_and_b32 s10, s4, 15
	s_mov_b64 s[8:9], -1
	s_and_b64 vcc, exec, s[6:7]
	v_cmp_ne_u32_e64 s[4:5], 1, v66
	s_cbranch_vccz .LBB0_347
	s_and_b64 vcc, exec, s[4:5]
	v_mov_b32_e32 v67, s10
	v_mov_b32_e32 v66, v227
	s_cbranch_vccnz .LBB0_346
	v_add_u32_e32 v66, s11, v17
	v_mul_u32_u24_e32 v67, 11, v66
	v_lshrrev_b32_e32 v67, 5, v67
	v_add3_u32 v66, v66, s62, v67
	v_and_b32_e32 v67, 15, v66
	v_mov_b32_e32 v66, s48

; #define LAS __attribute__((address_space(3)))
; __device__ __forceinline__ void run_desc(int tt, int g, int c, int R0, int& cg, int& Rg) {
;     if (tt < 4) { cg = c; Rg = R0 - 16 + 4 * tt + g; }
;     else if (tt < 7) { cg = (c + 4 * (tt - 3)) & 15; Rg = R0 - 4 + g; }
;     else if (tt < 10) { const int o = 4 * (tt - 7) + g; const int o3 = (o * 11) >> 5; cg = (c + 1 + o3 * 4 + (o - 3 * o3)) & 15; Rg = R0 - 1; }
;     else { cg = tt - 10; Rg = R0 + g; }
; }
; __device__ __forceinline__ bool tile_valid(int tt, int R0) {
;     if (tt < 4) return R0 - 16 + 4 * tt >= 0;
;     if (tt < 7) return R0 >= 4;
;     if (tt < 10) return R0 >= 1;
;     return true;
; }
; __device__ __forceinline__ int next_tile(int tt, int R0) { while (tt < 26 && !tile_valid(tt, R0)) ++tt; return tt; }
; __device__ __forceinline__ void attn_load_k(const AttnP& P, LAS unsigned char* lds, int hb, int tt, int c, int R0, int lane, bf16x8 (&kf)[4]) {
;     const int rho = lane & 31, h = lane >> 5;
;     const int gk_ = 2 * (rho >> 4) + ((rho >> 2) & 1), pk_ = 4 * ((rho >> 3) & 1) + (rho & 3);
;     if (tt < 10) {
;         int cg, Rg; run_desc(tt, gk_, c, R0, cg, Rg);
;         const bf16_t* kp = P.K + ((size_t)(hb * 16 + cg) * 128 + 8 * Rg + pk_) * 64 + 8 * h;
; #pragma unroll
;         for (int kk = 0; kk < 4; ++kk) kf[kk] = *(const bf16x8*)(kp + 16 * kk);
; __device__ __forceinline__ void tile_compute(const bf16x8 (&kf)[4], const bf16x8 (&vf)[2][2], const bf16x8 (&qf)[4], unsigned long long w0, unsigned long long w1,
;                                              float shift, f32x16& o0, f32x16& o1, f32x16& zacc, const bf16x8& ones) {
;     ...
;     for (int kk = 0; kk < 4; ++kk) st = __builtin_amdgcn_mfma_f32_32x32x16_bf16(kf[kk], qf[kk], st, 0, 0, 0);
.LBB0_417:
	s_waitcnt vmcnt(4)
	v_mfma_f32_32x32x16_bf16 v[66:81], v[106:109], v[86:89], 0
	v_mfma_f32_32x32x16_bf16 v[66:81], v[110:113], v[90:93], v[66:81]
	v_mfma_f32_32x32x16_bf16 v[66:81], v[114:117], v[94:97], v[66:81]
	v_mfma_f32_32x32x16_bf16 v[66:81], v[102:105], v[98:101], v[66:81]
	s_cmp_gt_i32 s36, 9
	s_cbranch_scc1 .Lattn_nopf_3
	s_lshl_b32 s4, s36, 2
	s_cmp_gt_i32 s36, 3
	s_mov_b64 s[0:1], -1
	s_cbranch_scc0 .LBB0_424
	s_cmp_gt_u32 s36, 6
	s_cbranch_scc0 .LBB0_421
	v_add_u32_e32 v246, s4, v223
	v_mul_u32_u24_e32 v247, 11, v246
	v_lshrrev_b32_e32 v247, 5, v247
	v_add3_u32 v246, v246, s62, v247
	v_and_b32_e32 v246, 15, v246
	s_mov_b64 s[0:1], 0
.LBB0_421:
	s_andn2_b64 vcc, exec, s[0:1]
	v_mov_b32_e32 v247, s48
	s_cbranch_vccnz .LBB0_423
	s_add_i32 s0, s4, s63
	s_and_b32 s0, s0, 15
	v_mov_b32_e32 v246, s0
	v_mov_b32_e32 v247, v224

; #define LAS __attribute__((address_space(3)))
; __device__ __forceinline__ void run_desc(int tt, int g, int c, int R0, int& cg, int& Rg) {
;     if (tt < 4) { cg = c; Rg = R0 - 16 + 4 * tt + g; }
;     else if (tt < 7) { cg = (c + 4 * (tt - 3)) & 15; Rg = R0 - 4 + g; }
;     else if (tt < 10) { const int o = 4 * (tt - 7) + g; const int o3 = (o * 11) >> 5; cg = (c + 1 + o3 * 4 + (o - 3 * o3)) & 15; Rg = R0 - 1; }
;     else { cg = tt - 10; Rg = R0 + g; }
; }
; __device__ __forceinline__ bool tile_valid(int tt, int R0) {
;     if (tt < 4) return R0 - 16 + 4 * tt >= 0;
;     if (tt < 7) return R0 >= 4;
;     if (tt < 10) return R0 >= 1;
;     return true;
; }
; __device__ __forceinline__ int next_tile(int tt, int R0) { while (tt < 26 && !tile_valid(tt, R0)) ++tt; return tt; }
; __device__ __forceinline__ void attn_load_k(const AttnP& P, LAS unsigned char* lds, int hb, int tt, int c, int R0, int lane, bf16x8 (&kf)[4]) {
;     const int rho = lane & 31, h = lane >> 5;
;     const int gk_ = 2 * (rho >> 4) + ((rho >> 2) & 1), pk_ = 4 * ((rho >> 3) & 1) + (rho & 3);
;     if (tt < 10) {
;         int cg, Rg; run_desc(tt, gk_, c, R0, cg, Rg);
;         const bf16_t* kp = P.K + ((size_t)(hb * 16 + cg) * 128 + 8 * Rg + pk_) * 64 + 8 * h;
; #pragma unroll
;         for (int kk = 0; kk < 4; ++kk) kf[kk] = *(const bf16x8*)(kp + 16 * kk);
.LBB0_424:
	s_andn2_b64 vcc, exec, s[0:1]
	s_cbranch_vccnz .LBB0_426
	v_add_u32_e32 v247, s4, v225
	v_mov_b32_e32 v246, s92
.LBB0_426:
	v_add_u32_e32 v190, s99, v246
	v_lshlrev_b32_e32 v246, 3, v247
	v_ashrrev_i32_e32 v247, 31, v246
	v_or_b32_e32 v247, v199, v247
	v_or_b32_e32 v246, v198, v246
	v_lshlrev_b64 v[248:249], 14, v[190:191]
	v_lshlrev_b64 v[246:247], 7, v[246:247]
	v_lshl_add_u64 v[248:249], v[206:207], 0, v[248:249]
	v_lshl_add_u64 v[246:247], v[248:249], 0, v[246:247]
	global_load_dwordx4 v[106:109], v[246:247], off
	global_load_dwordx4 v[110:113], v[246:247], off offset:32
	global_load_dwordx4 v[114:117], v[246:247], off offset:64
	global_load_dwordx4 v[102:105], v[246:247], off offset:96
	s_branch .Lattn_join_3

; __device__ __forceinline__ int next_tile(int tt, int R0) { while (tt < 26 && !tile_valid(tt, R0)) ++tt; return tt; }
; __device__ __forceinline__ void tile_compute(const bf16x8 (&kf)[4], const bf16x8 (&vf)[2][2], const bf16x8 (&qf)[4], unsigned long long w0, unsigned long long w1,
;                                              float shift, f32x16& o0, f32x16& o1, f32x16& zacc, const bf16x8& ones) {
;     ...
;     if (__builtin_amdgcn_readfirstlane(__builtin_bit_cast(int, shift)) != 0) {
; __device__ __forceinline__ void attn_task(const AttnP& P, LAS unsigned char* lds, int b, int hd, int qq, int c, float shift, int lane_in) {
;     ...
;             gi = next_tile(gi + 1, R0);
;             if (gi < 10) attn_load_k(P, lds, hb, gi, c, R0, lane, gk);
;             ph = 0;
.Lattn_join_3:
.LBB0_427:
	s_mov_b32 s8, 0
	s_mov_b32 s72, s36
	s_and_b64 vcc, exec, s[100:101]
	s_cbranch_vccnz .LBB0_334
	s_branch .Lattn_sub_3

; __device__ __forceinline__ void tile_compute(const bf16x8 (&kf)[4], const bf16x8 (&vf)[2][2], const bf16x8 (&qf)[4], unsigned long long w0, unsigned long long w1,
;                                              float shift, f32x16& o0, f32x16& o1, f32x16& zacc, const bf16x8& ones) {
;     ...
;     if (__builtin_amdgcn_readfirstlane(__builtin_bit_cast(int, shift)) != 0) {
;         asm volatile("" ::: "memory");
; #pragma unroll
;         for (int e = 0; e < 16; ++e) st[e] -= shift;
;     }
; __device__ __forceinline__ void attn_task(const AttnP& P, LAS unsigned char* lds, int b, int hd, int qq, int c, float shift, int lane_in) {
;     ...
;     const float rz = __builtin_amdgcn_rcpf(zacc[0]);
;     float ss = 0.f;
; #pragma unroll
;     for (int e = 0; e < 16; ++e) { o0[e] *= rz; o1[e] *= rz; ss += o0[e] * o0[e] + o1[e] * o1[e]; }
;     ss = xor32_sum(ss);
;     const size_t tok = (size_t)b * SEQ + c + 16 * (iq0 + q);
;     if (h == 0) P.ssqA[tok * 8 + hd] = ss;
.Lattn_sub_3:
	s_nop 10
	v_sub_f32_e32 v81, v81, v15
	v_sub_f32_e32 v80, v80, v16
	v_sub_f32_e32 v79, v79, v13
	v_sub_f32_e32 v78, v78, v14
	v_sub_f32_e32 v77, v77, v11
	v_sub_f32_e32 v76, v76, v12
	v_sub_f32_e32 v75, v75, v9
	v_sub_f32_e32 v74, v74, v10
	v_sub_f32_e32 v73, v73, v7
	v_sub_f32_e32 v72, v72, v8
	v_sub_f32_e32 v71, v71, v5
	v_sub_f32_e32 v70, v70, v6
	v_sub_f32_e32 v69, v69, v3
	v_sub_f32_e32 v68, v68, v4
	v_sub_f32_e32 v67, v67, v1
	v_sub_f32_e32 v66, v66, v2
	s_branch .LBB0_334
.LBB0_430:
	s_nop 10
	v_rcp_f32_e32 v52, v50
	v_cmp_gt_u32_e32 vcc, 32, v228
	v_pk_mul_f32 v[50:51], v[18:19], v[52:53] op_sel_hi:[1,0]
	v_pk_mul_f32 v[18:19], v[34:35], v[52:53] op_sel_hi:[1,0]
	v_pk_mul_f32 v[34:35], v[20:21], v[52:53] op_sel_hi:[1,0]
	v_pk_mul_f32 v[20:21], v[36:37], v[52:53] op_sel_hi:[1,0]
	v_pk_mul_f32 v[36:37], v[18:19], v[18:19]
	v_pk_mul_f32 v[54:55], v[20:21], v[20:21]
	v_pk_fma_f32 v[36:37], v[50:51], v[50:51], v[36:37]
	v_pk_fma_f32 v[54:55], v[34:35], v[34:35], v[54:55]
	v_pk_add_f32 v[36:37], v[36:37], v[36:37] op_sel:[0,1] op_sel_hi:[1,0]
	s_nop 0
	v_pk_add_f32 v[36:37], v[54:55], v[36:37]
	s_nop 0
	v_pk_add_f32 v[54:55], v[54:55], v[36:37] op_sel:[1,0] op_sel_hi:[0,1]
	v_pk_mul_f32 v[36:37], v[22:23], v[52:53] op_sel_hi:[1,0]
	v_pk_mul_f32 v[22:23], v[38:39], v[52:53] op_sel_hi:[1,0]
	s_nop 0
	v_pk_mul_f32 v[38:39], v[22:23], v[22:23]
	s_nop 0
	v_pk_fma_f32 v[38:39], v[36:37], v[36:37], v[38:39]
	s_nop 0
	v_pk_add_f32 v[54:55], v[38:39], v[54:55]
	s_nop 0
	v_pk_add_f32 v[54:55], v[38:39], v[54:55] op_sel:[1,0] op_sel_hi:[0,1]
	v_pk_mul_f32 v[38:39], v[24:25], v[52:53] op_sel_hi:[1,0]
	v_pk_mul_f32 v[24:25], v[40:41], v[52:53] op_sel_hi:[1,0]
	s_nop 0
	v_pk_mul_f32 v[40:41], v[24:25], v[24:25]
	s_nop 0
	v_pk_fma_f32 v[40:41], v[38:39], v[38:39], v[40:41]
	s_nop 0
	v_pk_add_f32 v[54:55], v[40:41], v[54:55]
	s_nop 0
	v_pk_add_f32 v[54:55], v[40:41], v[54:55] op_sel:[1,0] op_sel_hi:[0,1]
	v_pk_mul_f32 v[40:41], v[26:27], v[52:53] op_sel_hi:[1,0]
	v_pk_mul_f32 v[26:27], v[42:43], v[52:53] op_sel_hi:[1,0]
	s_nop 0
	v_pk_mul_f32 v[42:43], v[26:27], v[26:27]
	s_nop 0
	v_pk_fma_f32 v[42:43], v[40:41], v[40:41], v[42:43]
	s_nop 0
	v_pk_add_f32 v[54:55], v[42:43], v[54:55]
	s_nop 0
	v_pk_add_f32 v[54:55], v[42:43], v[54:55] op_sel:[1,0] op_sel_hi:[0,1]
	v_pk_mul_f32 v[42:43], v[28:29], v[52:53] op_sel_hi:[1,0]
	v_pk_mul_f32 v[28:29], v[44:45], v[52:53] op_sel_hi:[1,0]
	s_nop 0
	v_pk_mul_f32 v[44:45], v[28:29], v[28:29]
	s_nop 0
	v_pk_fma_f32 v[44:45], v[42:43], v[42:43], v[44:45]
	s_nop 0
	v_pk_add_f32 v[54:55], v[44:45], v[54:55]
	s_nop 0
	v_pk_add_f32 v[54:55], v[44:45], v[54:55] op_sel:[1,0] op_sel_hi:[0,1]
	v_pk_mul_f32 v[44:45], v[30:31], v[52:53] op_sel_hi:[1,0]
	v_pk_mul_f32 v[30:31], v[46:47], v[52:53] op_sel_hi:[1,0]
	s_nop 0
	v_pk_mul_f32 v[46:47], v[30:31], v[30:31]
	s_nop 0
	v_pk_fma_f32 v[46:47], v[44:45], v[44:45], v[46:47]
	s_nop 0
	v_pk_add_f32 v[54:55], v[46:47], v[54:55]
	s_nop 0
	v_pk_add_f32 v[54:55], v[46:47], v[54:55] op_sel:[1,0] op_sel_hi:[0,1]
	v_pk_mul_f32 v[46:47], v[32:33], v[52:53] op_sel_hi:[1,0]
	v_pk_mul_f32 v[32:33], v[48:49], v[52:53] op_sel_hi:[1,0]
	s_nop 0
	v_pk_mul_f32 v[48:49], v[32:33], v[32:33]
	s_nop 0
	v_pk_fma_f32 v[48:49], v[46:47], v[46:47], v[48:49]
	s_nop 0
	v_pk_add_f32 v[52:53], v[48:49], v[54:55]
	s_nop 0
	v_pk_add_f32 v[48:49], v[48:49], v[52:53] op_sel:[1,0] op_sel_hi:[0,1]
	v_mov_b32_e32 v49, v48
	v_or_b32_e32 v52, s38, v229
	s_nop 0
	v_permlane32_swap_b32_e32 v48, v49
	v_lshl_add_u32 v190, v52, 4, s25
	s_and_saveexec_b64 s[0:1], vcc
	s_cbranch_execz .LBB0_432
	v_lshlrev_b64 v[52:53], 5, v[190:191]
	v_lshl_add_u64 v[52:53], s[34:35], 0, v[52:53]
	s_lshl_b32 s4, s98, 2
	s_mov_b32 s5, s59
	v_lshl_add_u64 v[52:53], v[52:53], 0, s[4:5]
	v_add_f32_e32 v48, v48, v49
	global_store_dword v[52:53], v48, off

; #define LAS __attribute__((address_space(3)))
; __device__ __forceinline__ void tile_compute(const bf16x8 (&kf)[4], const bf16x8 (&vf)[2][2], const bf16x8 (&qf)[4], unsigned long long w0, unsigned long long w1,
;                                              float shift, f32x16& o0, f32x16& o1, f32x16& zacc, const bf16x8& ones) {
;     ...
;     for (int eg = 0; eg < 2; ++eg) {
;         const unsigned long long w = eg ? w1 : w0;
;         const unsigned wl = (unsigned)w, wh = (unsigned)(w >> 32);
;         float pv[8];
; #pragma unroll
;         for (int p = 0; p < 4; ++p) {
;             pv[p] = (float)((wl >> (8 * p)) & 0xffu) * __builtin_amdgcn_exp2f(st[8 * eg + p]);
;             pv[4 + p] = (float)((wh >> (8 * p)) & 0xffu) * __builtin_amdgcn_exp2f(st[8 * eg + 4 + p]);
;         }
; #pragma unroll
;         for (int p = 0; p < 4; ++p) pw[4 * eg + p] = pk2(pv[2 * p], pv[2 * p + 1]);
;     }
;     const bf16x8 pf0 = __builtin_bit_cast(bf16x8, (u32x4){pw[0], pw[1], pw[2], pw[3]});
;     const bf16x8 pf1 = __builtin_bit_cast(bf16x8, (u32x4){pw[4], pw[5], pw[6], pw[7]});
;     o0 = __builtin_amdgcn_mfma_f32_32x32x16_bf16(vf[0][0], pf0, o0, 0, 0, 0);
;     o1 = __builtin_amdgcn_mfma_f32_32x32x16_bf16(vf[1][0], pf0, o1, 0, 0, 0);
;     zacc = __builtin_amdgcn_mfma_f32_32x32x16_bf16(ones, pf0, zacc, 0, 0, 0);
;     o0 = __builtin_amdgcn_mfma_f32_32x32x16_bf16(vf[0][1], pf1, o0, 0, 0, 0);
;     o1 = __builtin_amdgcn_mfma_f32_32x32x16_bf16(vf[1][1], pf1, o1, 0, 0, 0);
;     zacc = __builtin_amdgcn_mfma_f32_32x32x16_bf16(ones, pf1, zacc, 0, 0, 0);
; __device__ __forceinline__ void attn_task(const AttnP& P, LAS unsigned char* lds, int b, int hd, int qq, int c, float shift, int lane_in) {
;     ...
;     unsigned long long Hp[2], Hn[2], Bp[2], Bn[2], mT0[2], mT3[2], mAp[2], mAn[2], mLp, mLn;
;     { const LAS unsigned long long* T = (const LAS unsigned long long*)(lds + LDS_ATAB + lane * 144);
;       Hp[0] = T[0]; Hp[1] = T[1]; Hn[0] = T[2]; Hn[1] = T[3]; Bp[0] = T[4]; Bp[1] = T[5]; Bn[0] = T[6]; Bn[1] = T[7];
;       mT0[0] = T[8]; mT0[1] = T[9]; mT3[0] = T[10]; mT3[1] = T[11]; mAp[0] = T[12]; mAp[1] = T[13]; mAn[0] = T[14]; mAn[1] = T[15]; mLp = T[16]; mLn = T[17]; }
;     f32x16 o0 = {}, o1 = {}, zacc = {};
;     bf16x8 ones = {0x3F80, 0x3F80, 0x3F80, 0x3F80, 0x3F80, 0x3F80, 0x3F80, 0x3F80}; asm volatile("" : "+v"(ones));
;     int li = 10, ph = 0;
.LBB0_436:
	s_movk_i32 s0, 0x90
	v_mul_lo_u32 v17, v224, s0
	v_add_u32_e32 v17, 0, v17
	v_add_u32_e32 v17, 0x24000, v17
	ds_read_b128 v[118:121], v17
	ds_read_b128 v[122:125], v17 offset:16
	ds_read_b128 v[126:129], v17 offset:32
	ds_read_b128 v[130:133], v17 offset:48
	ds_read_b128 v[134:137], v17 offset:64
	ds_read_b128 v[138:141], v17 offset:80
	ds_read_b128 v[142:145], v17 offset:96
	ds_read_b128 v[146:149], v17 offset:112
	ds_read_b128 v[150:153], v17 offset:128
	s_waitcnt lgkmcnt(8)
	v_mad_u64_u32 v[22:23], s[0:1], v118, 3, 0
	v_mov_b32_e32 v24, v23
	v_mad_u64_u32 v[24:25], s[0:1], v119, 3, v[24:25]
	s_waitcnt lgkmcnt(7)
	v_sub_co_u32_e32 v22, vcc, v22, v122
	v_mov_b64_e32 v[156:157], v[84:85]
	s_nop 0
	v_subb_co_u32_e32 v23, vcc, v24, v123, vcc
	s_waitcnt lgkmcnt(5)
	v_lshl_add_u64 v[202:203], v[22:23], 0, v[130:131]
	v_mad_u64_u32 v[22:23], s[0:1], v120, 3, 0
	v_mov_b32_e32 v24, v23
	v_mad_u64_u32 v[24:25], s[0:1], v121, 3, v[24:25]
	v_sub_co_u32_e32 v22, vcc, v22, v124
	s_movk_i32 s0, 0xfec0
	v_or_b32_e32 v17, 0xffffffe4, v20
	v_or_b32_e32 v226, s57, v20
	v_or3_b32 v227, s56, v20, -16
	v_lshlrev_b32_e32 v20, 4, v225
	v_add_u32_e32 v230, 2, v223
	v_subb_co_u32_e32 v23, vcc, v24, v125, vcc
	v_or3_b32 v234, v190, v21, s0
	v_lshl_add_u64 v[206:207], v[18:19], 1, s[50:51]
	v_mov_b32_e32 v21, v191
	v_mov_b32_e32 v18, 0
	v_mov_b64_e32 v[154:155], v[82:83]
	v_lshl_add_u32 v200, v223, 4, 0
	v_add_u32_e32 v228, s93, v20
	v_add_u32_e32 v229, s57, v223
	v_add_u32_e32 v231, s57, v230
	v_lshl_add_u64 v[204:205], v[22:23], 0, v[132:133]
	v_subrev_u32_e32 v232, 26, v223
	s_mov_b32 s56, 10
	v_lshl_add_u32 v233, v223, 10, v214
	v_lshl_add_u64 v[208:209], s[52:53], 0, v[20:21]
	s_mov_b32 s8, 0
	s_mov_b64 s[0:1], s[60:61]
	v_mov_b32_e32 v19, v18
	v_mov_b32_e32 v20, v18
	v_mov_b32_e32 v21, v18
	v_mov_b32_e32 v22, v18
	v_mov_b32_e32 v23, v18
	v_mov_b32_e32 v24, v18
	v_mov_b32_e32 v25, v18
	v_mov_b32_e32 v26, v18
	v_mov_b32_e32 v27, v18
	v_mov_b32_e32 v28, v18
	v_mov_b32_e32 v29, v18
	v_mov_b32_e32 v30, v18
	v_mov_b32_e32 v31, v18
	v_mov_b32_e32 v32, v18
	v_mov_b32_e32 v33, v18
	v_mov_b32_e32 v34, v18
	v_mov_b32_e32 v35, v18
	v_mov_b32_e32 v36, v18
	v_mov_b32_e32 v37, v18
	v_mov_b32_e32 v38, v18
	v_mov_b32_e32 v39, v18
	v_mov_b32_e32 v40, v18
	v_mov_b32_e32 v41, v18
	v_mov_b32_e32 v42, v18
	v_mov_b32_e32 v43, v18
	v_mov_b32_e32 v44, v18
	v_mov_b32_e32 v45, v18
	v_mov_b32_e32 v46, v18
	v_mov_b32_e32 v47, v18
	v_mov_b32_e32 v48, v18
	v_mov_b32_e32 v49, v18
	v_mov_b32_e32 v50, v18
	v_mov_b32_e32 v51, v18
	v_mov_b32_e32 v52, v18
	v_mov_b32_e32 v53, v18
	v_mov_b32_e32 v54, v18
	v_mov_b32_e32 v55, v18
	v_mov_b32_e32 v56, v18
	v_mov_b32_e32 v57, v18
	v_mov_b32_e32 v58, v18
	v_mov_b32_e32 v59, v18
	v_mov_b32_e32 v60, v18
	v_mov_b32_e32 v61, v18
	v_mov_b32_e32 v62, v18
	v_mov_b32_e32 v63, v18
	v_mov_b32_e32 v64, v18
	v_mov_b32_e32 v65, v18
	v_mul_lo_u32 v245, v234, s71
	v_add_u32_e32 v245, v245, v200
	s_waitcnt vmcnt(0)
	s_branch .LBB0_438
.LBB0_437:
	v_cvt_f32_ubyte1_e32 v175, v212
	v_cvt_f32_ubyte0_e32 v174, v212
	s_nop 3
	v_exp_f32_e32 v66, v66
	s_nop 3
	v_exp_f32_e32 v67, v67
	v_exp_f32_e32 v70, v70
	v_exp_f32_e32 v71, v71
	v_exp_f32_e32 v68, v68
	v_exp_f32_e32 v69, v69
	v_exp_f32_e32 v72, v72
	v_exp_f32_e32 v73, v73
	v_pk_mul_f32 v[66:67], v[66:67], v[174:175]
	v_cvt_f32_ubyte1_e32 v175, v213
	v_cvt_f32_ubyte0_e32 v174, v213
	v_pk_mul_f32 v[70:71], v[70:71], v[174:175]
	v_cvt_f32_ubyte3_e32 v175, v212
	v_cvt_f32_ubyte2_e32 v174, v212
	v_pk_mul_f32 v[68:69], v[68:69], v[174:175]
	v_cvt_f32_ubyte3_e32 v175, v213
	v_cvt_f32_ubyte2_e32 v174, v213
	v_pk_mul_f32 v[72:73], v[72:73], v[174:175]
	v_cvt_pk_bf16_f32 v66, v66, v67
	v_cvt_pk_bf16_f32 v67, v68, v69
	v_cvt_pk_bf16_f32 v68, v70, v71
	v_exp_f32_e32 v70, v74
	v_exp_f32_e32 v71, v75
	v_cvt_pk_bf16_f32 v69, v72, v73
	v_exp_f32_e32 v72, v78
	v_exp_f32_e32 v73, v79
	s_waitcnt vmcnt(4)
	v_mfma_f32_32x32x16_bf16 v[18:33], v[162:165], v[66:69], v[18:33]
	v_cvt_f32_ubyte1_e32 v75, v210
	v_cvt_f32_ubyte0_e32 v74, v210
	v_mul_f32_e64 v70, v70, v74
	v_mul_f32_e64 v71, v71, v75
	v_cvt_f32_ubyte1_e32 v75, v211
	v_cvt_f32_ubyte0_e32 v74, v211
	v_pk_mul_f32 v[72:73], v[72:73], v[74:75]
	v_exp_f32_e32 v74, v76
	v_mfma_f32_32x32x16_bf16 v[34:49], v[158:161], v[66:69], v[34:49]
	v_exp_f32_e32 v75, v77
	v_exp_f32_e32 v76, v80
	v_exp_f32_e32 v77, v81
	v_cvt_f32_ubyte3_e32 v79, v210
	v_cvt_f32_ubyte2_e32 v78, v210
	v_pk_mul_f32 v[74:75], v[74:75], v[78:79]
	s_cmp_lt_i32 s56, 26
	v_mfma_f32_32x32x16_bf16 v[50:65], v[154:157], v[66:69], v[50:65]
	v_cvt_f32_ubyte3_e32 v67, v211
	v_cvt_f32_ubyte2_e32 v66, v211
	v_mul_f32_e64 v76, v76, v66
	v_mul_f32_e64 v77, v77, v67
	v_cvt_pk_bf16_f32 v66, v70, v71
	v_cvt_pk_bf16_f32 v67, v74, v75
	v_cvt_pk_bf16_f32 v68, v72, v73
	v_cvt_pk_bf16_f32 v69, v76, v77
	s_cselect_b64 s[4:5], -1, 0
	s_cmp_lt_i32 s24, 10
	v_mfma_f32_32x32x16_bf16 v[18:33], v[166:169], v[66:69], v[18:33]
	s_cselect_b64 s[0:1], -1, 0
	s_or_b64 s[4:5], s[4:5], s[0:1]
	s_and_b64 vcc, exec, s[4:5]
	v_mfma_f32_32x32x16_bf16 v[34:49], v[170:173], v[66:69], v[34:49]
	v_mfma_f32_32x32x16_bf16 v[50:65], v[154:157], v[66:69], v[50:65]
	s_cbranch_vccz .LBB0_533

; __device__ __forceinline__ void attn_task(const AttnP& P, LAS unsigned char* lds, int b, int hd, int qq, int c, float shift, int lane_in) {
;     ...
;         if (gi < 10 && (ph >= 2 || li >= 26)) {
;             attn_load_v(P, lds, hb, gi, c, R0, lane, vf);
; #pragma unroll
;             for (int kk = 0; kk < 4; ++kk) kf[kk] = gk[kk];
;             if (gi < 4) {
;                 if (gi == 0) { w0 = mT0[0]; w1 = mT0[1]; } else if (gi == 3) { w0 = mT3[0]; w1 = mT3[1]; } else { w0 = 0x0101010101010101ull; w1 = 0x0101010101010101ull; }
;             } else if (gi < 7) {
;                 const bool pos = c > ((c + 4 * (gi - 3)) & 15);
;                 w0 = pos ? mAp[0] : mAn[0]; w1 = pos ? mAp[1] : mAn[1];
;             } else {
;                 { int cg, Rg; run_desc(gi, h, c, R0, cg, Rg); w0 = (c > cg) ? mLp : mLn; }
;                 { int cg, Rg; run_desc(gi, 2 + h, c, R0, cg, Rg); w1 = (c > cg) ? mLp : mLn; }
;             }
.LBB0_445:
	s_and_b64 vcc, exec, s[0:1]
	s_cbranch_vccz .LBB0_506
	s_cmp_gt_i32 s24, 3
	s_cselect_b64 s[6:7], -1, 0
	s_lshl_b32 s25, s24, 2
	s_sub_i32 s11, s25, 28
	s_cmp_gt_u32 s24, 6
	s_cselect_b64 s[0:1], -1, 0
	s_add_i32 s4, s25, s70
	s_waitcnt lgkmcnt(3)
	v_cndmask_b32_e64 v66, 0, 1, s[0:1]
	s_and_b32 s10, s4, 15
	s_mov_b64 s[8:9], -1
	s_and_b64 vcc, exec, s[6:7]
	v_cmp_ne_u32_e64 s[4:5], 1, v66
	s_cbranch_vccz .LBB0_450
	s_and_b64 vcc, exec, s[4:5]
	v_mov_b32_e32 v67, s10
	v_mov_b32_e32 v66, v229
	s_cbranch_vccnz .LBB0_449
	v_add_u32_e32 v66, s11, v223
	v_mul_u32_u24_e32 v67, 11, v66
	v_lshrrev_b32_e32 v67, 5, v67
	v_add3_u32 v66, v66, s65, v67
	v_and_b32_e32 v67, 15, v66
	v_mov_b32_e32 v66, s48

; #define LAS __attribute__((address_space(3)))
; __device__ __forceinline__ void run_desc(int tt, int g, int c, int R0, int& cg, int& Rg) {
;     if (tt < 4) { cg = c; Rg = R0 - 16 + 4 * tt + g; }
;     else if (tt < 7) { cg = (c + 4 * (tt - 3)) & 15; Rg = R0 - 4 + g; }
;     else if (tt < 10) { const int o = 4 * (tt - 7) + g; const int o3 = (o * 11) >> 5; cg = (c + 1 + o3 * 4 + (o - 3 * o3)) & 15; Rg = R0 - 1; }
;     else { cg = tt - 10; Rg = R0 + g; }
; }
; __device__ __forceinline__ bool tile_valid(int tt, int R0) {
;     if (tt < 4) return R0 - 16 + 4 * tt >= 0;
;     if (tt < 7) return R0 >= 4;
;     if (tt < 10) return R0 >= 1;
;     return true;
; }
; __device__ __forceinline__ int next_tile(int tt, int R0) { while (tt < 26 && !tile_valid(tt, R0)) ++tt; return tt; }
; __device__ __forceinline__ void attn_load_k(const AttnP& P, LAS unsigned char* lds, int hb, int tt, int c, int R0, int lane, bf16x8 (&kf)[4]) {
;     const int rho = lane & 31, h = lane >> 5;
;     const int gk_ = 2 * (rho >> 4) + ((rho >> 2) & 1), pk_ = 4 * ((rho >> 3) & 1) + (rho & 3);
;     if (tt < 10) {
;         int cg, Rg; run_desc(tt, gk_, c, R0, cg, Rg);
;         const bf16_t* kp = P.K + ((size_t)(hb * 16 + cg) * 128 + 8 * Rg + pk_) * 64 + 8 * h;
; #pragma unroll
;         for (int kk = 0; kk < 4; ++kk) kf[kk] = *(const bf16x8*)(kp + 16 * kk);
; __device__ __forceinline__ void tile_compute(const bf16x8 (&kf)[4], const bf16x8 (&vf)[2][2], const bf16x8 (&qf)[4], unsigned long long w0, unsigned long long w1,
;                                              float shift, f32x16& o0, f32x16& o1, f32x16& zacc, const bf16x8& ones) {
;     ...
;     for (int kk = 0; kk < 4; ++kk) st = __builtin_amdgcn_mfma_f32_32x32x16_bf16(kf[kk], qf[kk], st, 0, 0, 0);
.LBB0_520:
	s_waitcnt vmcnt(4)
	v_mfma_f32_32x32x16_bf16 v[66:81], v[106:109], v[86:89], 0
	v_mfma_f32_32x32x16_bf16 v[66:81], v[110:113], v[90:93], v[66:81]
	v_mfma_f32_32x32x16_bf16 v[66:81], v[114:117], v[94:97], v[66:81]
	v_mfma_f32_32x32x16_bf16 v[66:81], v[102:105], v[98:101], v[66:81]
	s_cmp_gt_i32 s28, 9
	s_cbranch_scc1 .Lattn_nopf_4
	s_lshl_b32 s4, s28, 2
	s_cmp_gt_i32 s28, 3
	s_mov_b64 s[0:1], -1
	s_cbranch_scc0 .LBB0_527
	s_cmp_gt_u32 s28, 6
	s_cbranch_scc0 .LBB0_524
	v_add_u32_e32 v246, s4, v17
	v_mul_u32_u24_e32 v247, 11, v246
	v_lshrrev_b32_e32 v247, 5, v247
	v_add3_u32 v246, v246, s65, v247
	v_and_b32_e32 v246, 15, v246
	s_mov_b64 s[0:1], 0
.LBB0_524:
	s_andn2_b64 vcc, exec, s[0:1]
	v_mov_b32_e32 v247, s48
	s_cbranch_vccnz .LBB0_526
	s_add_i32 s0, s4, s70
	s_and_b32 s0, s0, 15
	v_mov_b32_e32 v246, s0
	v_mov_b32_e32 v247, v226

; __device__ __forceinline__ void run_desc(int tt, int g, int c, int R0, int& cg, int& Rg) {
;     if (tt < 4) { cg = c; Rg = R0 - 16 + 4 * tt + g; }
;     else if (tt < 7) { cg = (c + 4 * (tt - 3)) & 15; Rg = R0 - 4 + g; }
;     else if (tt < 10) { const int o = 4 * (tt - 7) + g; const int o3 = (o * 11) >> 5; cg = (c + 1 + o3 * 4 + (o - 3 * o3)) & 15; Rg = R0 - 1; }
;     else { cg = tt - 10; Rg = R0 + g; }
.LBB0_527:
	s_andn2_b64 vcc, exec, s[0:1]
	s_cbranch_vccnz .LBB0_529
	v_add_u32_e32 v247, s4, v227
	v_mov_b32_e32 v246, s64

; __device__ __forceinline__ int next_tile(int tt, int R0) { while (tt < 26 && !tile_valid(tt, R0)) ++tt; return tt; }
; __device__ __forceinline__ void tile_compute(const bf16x8 (&kf)[4], const bf16x8 (&vf)[2][2], const bf16x8 (&qf)[4], unsigned long long w0, unsigned long long w1,
;                                              float shift, f32x16& o0, f32x16& o1, f32x16& zacc, const bf16x8& ones) {
;     ...
;     if (__builtin_amdgcn_readfirstlane(__builtin_bit_cast(int, shift)) != 0) {
; __device__ __forceinline__ void attn_task(const AttnP& P, LAS unsigned char* lds, int b, int hd, int qq, int c, float shift, int lane_in) {
;     ...
;             gi = next_tile(gi + 1, R0);
;             if (gi < 10) attn_load_k(P, lds, hb, gi, c, R0, lane, gk);
;             ph = 0;
.Lattn_join_4:
.LBB0_530:
	s_mov_b32 s8, 0
	s_mov_b32 s24, s28
	s_and_b64 vcc, exec, s[100:101]
	s_cbranch_vccnz .LBB0_437
	s_branch .Lattn_sub_4

; __device__ __forceinline__ void tile_compute(const bf16x8 (&kf)[4], const bf16x8 (&vf)[2][2], const bf16x8 (&qf)[4], unsigned long long w0, unsigned long long w1,
;                                              float shift, f32x16& o0, f32x16& o1, f32x16& zacc, const bf16x8& ones) {
;     ...
;     if (__builtin_amdgcn_readfirstlane(__builtin_bit_cast(int, shift)) != 0) {
;         asm volatile("" ::: "memory");
; #pragma unroll
;         for (int e = 0; e < 16; ++e) st[e] -= shift;
;     }
; __device__ __forceinline__ void attn_task(const AttnP& P, LAS unsigned char* lds, int b, int hd, int qq, int c, float shift, int lane_in) {
;     ...
;     const float rz = __builtin_amdgcn_rcpf(zacc[0]);
;     float ss = 0.f;
; #pragma unroll
;     for (int e = 0; e < 16; ++e) { o0[e] *= rz; o1[e] *= rz; ss += o0[e] * o0[e] + o1[e] * o1[e]; }
;     ss = xor32_sum(ss);
;     const size_t tok = (size_t)b * SEQ + c + 16 * (iq0 + q);
;     if (h == 0) P.ssqA[tok * 8 + hd] = ss;
.Lattn_sub_4:
	s_nop 10
	v_sub_f32_e32 v81, v81, v15
	v_sub_f32_e32 v80, v80, v16
	v_sub_f32_e32 v79, v79, v13
	v_sub_f32_e32 v78, v78, v14
	v_sub_f32_e32 v77, v77, v11
	v_sub_f32_e32 v76, v76, v12
	v_sub_f32_e32 v75, v75, v9
	v_sub_f32_e32 v74, v74, v10
	v_sub_f32_e32 v73, v73, v7
	v_sub_f32_e32 v72, v72, v8
	v_sub_f32_e32 v71, v71, v5
	v_sub_f32_e32 v70, v70, v6
	v_sub_f32_e32 v69, v69, v3
	v_sub_f32_e32 v68, v68, v4
	v_sub_f32_e32 v67, v67, v1
	v_sub_f32_e32 v66, v66, v2
	s_branch .LBB0_437
.LBB0_533:
	s_nop 10
	v_rcp_f32_e32 v50, v50
	v_cmp_gt_u32_e32 vcc, 32, v224
	v_pk_mul_f32 v[2:3], v[34:35], v[50:51] op_sel_hi:[1,0]
	v_pk_mul_f32 v[4:5], v[18:19], v[50:51] op_sel_hi:[1,0]
	v_pk_mul_f32 v[6:7], v[36:37], v[50:51] op_sel_hi:[1,0]
	v_pk_mul_f32 v[8:9], v[2:3], v[2:3]
	v_pk_mul_f32 v[10:11], v[20:21], v[50:51] op_sel_hi:[1,0]
	v_pk_fma_f32 v[8:9], v[4:5], v[4:5], v[8:9]
	v_pk_mul_f32 v[12:13], v[6:7], v[6:7]
	v_pk_add_f32 v[8:9], v[8:9], v[8:9] op_sel:[0,1] op_sel_hi:[1,0]
	v_pk_fma_f32 v[12:13], v[10:11], v[10:11], v[12:13]
	v_pk_mul_f32 v[32:33], v[32:33], v[50:51] op_sel_hi:[1,0]
	v_pk_add_f32 v[8:9], v[12:13], v[8:9]
	s_nop 0
	v_pk_add_f32 v[14:15], v[12:13], v[8:9] op_sel:[1,0] op_sel_hi:[0,1]
	v_pk_mul_f32 v[8:9], v[38:39], v[50:51] op_sel_hi:[1,0]
	v_pk_mul_f32 v[12:13], v[22:23], v[50:51] op_sel_hi:[1,0]
	v_pk_mul_f32 v[16:17], v[8:9], v[8:9]
	s_nop 0
	v_pk_fma_f32 v[16:17], v[12:13], v[12:13], v[16:17]
	s_nop 0
	v_pk_add_f32 v[14:15], v[16:17], v[14:15]
	s_nop 0
	v_pk_add_f32 v[18:19], v[16:17], v[14:15] op_sel:[1,0] op_sel_hi:[0,1]
	v_pk_mul_f32 v[14:15], v[40:41], v[50:51] op_sel_hi:[1,0]
	v_pk_mul_f32 v[16:17], v[24:25], v[50:51] op_sel_hi:[1,0]
	v_pk_mul_f32 v[20:21], v[14:15], v[14:15]
	s_nop 0
	v_pk_fma_f32 v[20:21], v[16:17], v[16:17], v[20:21]
	s_nop 0
	v_pk_add_f32 v[18:19], v[20:21], v[18:19]
	s_nop 0
	v_pk_add_f32 v[22:23], v[20:21], v[18:19] op_sel:[1,0] op_sel_hi:[0,1]
	v_pk_mul_f32 v[18:19], v[42:43], v[50:51] op_sel_hi:[1,0]
	v_pk_mul_f32 v[20:21], v[26:27], v[50:51] op_sel_hi:[1,0]
	v_pk_mul_f32 v[24:25], v[18:19], v[18:19]
	s_nop 0
	v_pk_fma_f32 v[24:25], v[20:21], v[20:21], v[24:25]
	s_nop 0
	v_pk_add_f32 v[22:23], v[24:25], v[22:23]
	s_nop 0
	v_pk_add_f32 v[26:27], v[24:25], v[22:23] op_sel:[1,0] op_sel_hi:[0,1]
	v_pk_mul_f32 v[22:23], v[44:45], v[50:51] op_sel_hi:[1,0]
	v_pk_mul_f32 v[24:25], v[28:29], v[50:51] op_sel_hi:[1,0]
	v_pk_mul_f32 v[28:29], v[22:23], v[22:23]
	s_nop 0
	v_pk_fma_f32 v[28:29], v[24:25], v[24:25], v[28:29]
	s_nop 0
	v_pk_add_f32 v[26:27], v[28:29], v[26:27]
	s_nop 0
	v_pk_add_f32 v[34:35], v[28:29], v[26:27] op_sel:[1,0] op_sel_hi:[0,1]
	v_pk_mul_f32 v[26:27], v[46:47], v[50:51] op_sel_hi:[1,0]
	v_pk_mul_f32 v[28:29], v[30:31], v[50:51] op_sel_hi:[1,0]
	v_pk_mul_f32 v[30:31], v[26:27], v[26:27]
	s_nop 0
	v_pk_fma_f32 v[30:31], v[28:29], v[28:29], v[30:31]
	s_nop 0
	v_pk_add_f32 v[34:35], v[30:31], v[34:35]
	s_nop 0
	v_pk_add_f32 v[34:35], v[30:31], v[34:35] op_sel:[1,0] op_sel_hi:[0,1]
	v_pk_mul_f32 v[30:31], v[48:49], v[50:51] op_sel_hi:[1,0]
	s_nop 0
	v_pk_mul_f32 v[36:37], v[30:31], v[30:31]
	s_nop 0
	v_pk_fma_f32 v[36:37], v[32:33], v[32:33], v[36:37]
	s_nop 0
	v_pk_add_f32 v[34:35], v[36:37], v[34:35]
	s_nop 0
	v_pk_add_f32 v[34:35], v[36:37], v[34:35] op_sel:[1,0] op_sel_hi:[0,1]
	v_mov_b32_e32 v1, v34
	v_or_b32_e32 v35, s38, v225
	s_nop 0
	v_permlane32_swap_b32_e32 v34, v1
	v_lshl_add_u32 v190, v35, 4, s21
	s_and_saveexec_b64 s[0:1], vcc
	s_cbranch_execz .LBB0_168
	v_lshlrev_b64 v[36:37], 5, v[190:191]
	v_lshl_add_u64 v[36:37], s[34:35], 0, v[36:37]
	s_lshl_b32 s4, s98, 2
	s_mov_b32 s5, s59
	v_lshl_add_u64 v[36:37], v[36:37], 0, s[4:5]
	v_add_f32_e32 v1, v34, v1
	global_store_dword v[36:37], v1, off
	s_branch .LBB0_168
